# MLA tile loop: the two wave-uniform exec guards done as scalar compares against the wave's first / last query row kept in two scalars (no VALU compare, no VALU->SALU mask hand-off)
# speedup vs baseline: 1.0028x; 1.0028x over previous
; DI float bf_lo(unsigned u) { return __uint_as_float(u << 16); }
; DI float bf_hi(unsigned u) { return __uint_as_float(u & 0xffff0000u); }
;     ...
;     f32x16 o[2];
; #pragma unroll
;     for (int d = 0; d < 2; ++d)
; #pragma unroll
;         for (int r = 0; r < 16; ++r) o[d][r] = 0.f;
;     float m = -INFINITY, lsum = 0.f;
;     float qkb = 0.f; bool wdone = false;
;     if (FOX) {
;         float q2 = 0.f;
; #pragma unroll
;         for (int ks = 0; ks < 4; ++ks) {
;             const u32x4 w = __builtin_bit_cast(u32x4, qf[ks]);
; #pragma unroll
;             for (int e = 0; e < 4; ++e) { const float a = bf_lo(w[e]), b2 = bf_hi(w[e]); q2 += a * a + b2 * b2; }
;         }
;         { const auto sw = __builtin_amdgcn_permlane32_swap(__float_as_uint(q2), __float_as_uint(q2), false, false);
;           q2 = __uint_as_float(sw[0]) + __uint_as_float(sw[1]); }
;         qkb = sqrtf(q2 * kmax2) * 1.01f + 0.01f;
;     }
;     constexpr int NK2 = (64 * KCH + NT - 1) / NT;
;     u32x4 kr[NK2]; u32x4 vr; float br = 0.f;
;     auto gload = [&](int j) {
; #pragma unroll
;         for (int r = 0; r < NK2; ++r) {
;             const int c = tid + NT * r;
;             if (c < 64 * KCH) { const int row = c / KCH, ch = c - row * KCH; kr[r] = *(const u32x4*)(kbase + (size_t)(64 * j + row) * ldk + ch * 8); }
;         }
;         { const int row = tid >> 3, ch = tid & 7; vr = *(const u32x4*)(vt + (size_t)row * LP + 64 * j + ch * 8); }
;         if (FOX) { if (tid < 64) br = bias[64 * j + tid]; }
;     };
;     auto lstore = [&](int st) {
;         unsigned char* base = lds + st * STG;
; #pragma unroll
;         for (int r = 0; r < NK2; ++r) {
;             const int c = tid + NT * r;
;             if (c < 64 * KCH) { const int row = c / KCH, ch = c - row * KCH; *(u32x4*)(base + row * KROW + ch * 16) = kr[r]; }
;         }
;         { const int row = tid >> 3, ch = tid & 7; unsigned char* d = base + KBYTES + row * VROW + ch * 16;
;           *(u32x2*)d = (u32x2){vr[0], vr[1]}; *(u32x2*)(d + 8) = (u32x2){vr[2], vr[3]}; }
;         if (FOX) { if (tid < 64) *(float*)(base + KBYTES + VBYTES + tid * 4) = br; }
;     };
;     const int jlast = nkt - 1;
;     gload(jlast); lstore(0);
;     __syncthreads();
;     m = -1e30f;
.LBB0_745:
	s_or_b64 exec, exec, s[10:11]
	s_and_b32 s10, s13, 0x1fc0
	v_add_u32_e32 v1, s12, v151
	v_subrev_u32_e32 v219, s10, v1
	v_add_u32_e32 v1, s10, v184
	s_xor_b64 s[48:49], s[8:9], -1
	v_mad_i64_i32 v[176:177], s[8:9], v1, s70, v[172:173]
	v_add_u32_e32 v1, s10, v189
	v_mov_b32_e32 v14, v0
	v_mov_b32_e32 v15, v0
	v_mad_i64_i32 v[178:179], s[8:9], v1, s70, v[174:175]
	v_mov_b32_e32 v1, v0
	v_mov_b32_e32 v2, v0
	v_mov_b32_e32 v3, v0
	v_mov_b32_e32 v4, v0
	v_mov_b32_e32 v5, v0
	v_mov_b32_e32 v6, v0
	v_mov_b32_e32 v7, v0
	v_mov_b32_e32 v8, v0
	v_mov_b32_e32 v9, v0
	v_mov_b32_e32 v10, v0
	v_mov_b32_e32 v11, v0
	v_mov_b32_e32 v12, v0
	v_mov_b32_e32 v13, v0
	v_mov_b64_e32 v[32:33], v[14:15]
	v_mov_b64_e32 v[30:31], v[12:13]
	v_mov_b64_e32 v[28:29], v[10:11]
	v_mov_b64_e32 v[26:27], v[8:9]
	v_mov_b64_e32 v[24:25], v[6:7]
	v_mov_b64_e32 v[22:23], v[4:5]
	v_mov_b64_e32 v[20:21], v[2:3]
	v_mov_b64_e32 v[18:19], v[0:1]
	v_mov_b64_e32 v[16:17], v[14:15]
	s_lshr_b32 s2, s13, 6
	v_add_u32_e32 v218, 31, v159
	v_readfirstlane_b32 s73, v159
	s_nop 1
	s_add_i32 s72, s73, 31
	s_sub_i32 s42, s10, 64
	s_mov_b32 s60, 0
	v_mov_b32_e32 v220, 0
	v_mov_b32_e32 v248, 0
	v_mov_b32_e32 v249, 0
	v_mov_b32_e32 v250, 0
	v_mov_b32_e32 v251, 0
	v_mov_b32_e32 v252, 0
	v_mov_b32_e32 v253, 0
	v_mov_b32_e32 v254, 0
	v_mov_b32_e32 v255, 0
	v_mov_b32_e32 v221, 0xf149f2ca
	v_mov_b32_e32 v230, 0
	v_mov_b32_e32 v231, 0
	v_mov_b32_e32 v232, 0
	v_mov_b32_e32 v233, 0
	v_mov_b32_e32 v234, 0
	v_mov_b32_e32 v235, 0
	v_mov_b32_e32 v236, 0
	v_mov_b32_e32 v237, 0
	v_mov_b32_e32 v238, 0
	v_mov_b32_e32 v239, 0
	v_mov_b32_e32 v240, 0
	v_mov_b32_e32 v241, 0
	v_mov_b32_e32 v242, 0
	v_mov_b32_e32 v243, 0
	v_mov_b32_e32 v244, 0
	v_mov_b32_e32 v245, 0
	v_mov_b32_e32 v246, 0
	v_mov_b64_e32 v[14:15], v[12:13]
	v_mov_b64_e32 v[12:13], v[10:11]
	v_mov_b64_e32 v[10:11], v[8:9]
	v_mov_b64_e32 v[8:9], v[6:7]
	v_mov_b64_e32 v[6:7], v[4:5]
	v_mov_b64_e32 v[4:5], v[2:3]
	v_mov_b64_e32 v[2:3], v[0:1]
	s_waitcnt vmcnt(0)
	ds_write2_b64 v213, v[98:99], v[100:101] offset1:1
	s_waitcnt lgkmcnt(0)
	s_barrier
	s_branch .LBB0_748

; DI float bf_lo(unsigned u) { return __uint_as_float(u << 16); }
; DI float bf_hi(unsigned u) { return __uint_as_float(u & 0xffff0000u); }
;     ...
;     f32x16 o[2];
; #pragma unroll
;     for (int d = 0; d < 2; ++d)
; #pragma unroll
;         for (int r = 0; r < 16; ++r) o[d][r] = 0.f;
;     float m = -INFINITY, lsum = 0.f;
;     float qkb = 0.f; bool wdone = false;
;     if (FOX) {
;         float q2 = 0.f;
; #pragma unroll
;         for (int ks = 0; ks < 4; ++ks) {
;             const u32x4 w = __builtin_bit_cast(u32x4, qf[ks]);
; #pragma unroll
;             for (int e = 0; e < 4; ++e) { const float a = bf_lo(w[e]), b2 = bf_hi(w[e]); q2 += a * a + b2 * b2; }
;         }
;         { const auto sw = __builtin_amdgcn_permlane32_swap(__float_as_uint(q2), __float_as_uint(q2), false, false);
;           q2 = __uint_as_float(sw[0]) + __uint_as_float(sw[1]); }
;         qkb = sqrtf(q2 * kmax2) * 1.01f + 0.01f;
;     }
;     constexpr int NK2 = (64 * KCH + NT - 1) / NT;
;     u32x4 kr[NK2]; u32x4 vr; float br = 0.f;
;     auto gload = [&](int j) {
; #pragma unroll
;         for (int r = 0; r < NK2; ++r) {
;             const int c = tid + NT * r;
;             if (c < 64 * KCH) { const int row = c / KCH, ch = c - row * KCH; kr[r] = *(const u32x4*)(kbase + (size_t)(64 * j + row) * ldk + ch * 8); }
;         }
;         { const int row = tid >> 3, ch = tid & 7; vr = *(const u32x4*)(vt + (size_t)row * LP + 64 * j + ch * 8); }
;         if (FOX) { if (tid < 64) br = bias[64 * j + tid]; }
;     };
;     auto lstore = [&](int st) {
;         unsigned char* base = lds + st * STG;
; #pragma unroll
;         for (int r = 0; r < NK2; ++r) {
;             const int c = tid + NT * r;
;             if (c < 64 * KCH) { const int row = c / KCH, ch = c - row * KCH; *(u32x4*)(base + row * KROW + ch * 16) = kr[r]; }
;         }
;         { const int row = tid >> 3, ch = tid & 7; unsigned char* d = base + KBYTES + row * VROW + ch * 16;
;           *(u32x2*)d = (u32x2){vr[0], vr[1]}; *(u32x2*)(d + 8) = (u32x2){vr[2], vr[3]}; }
;         if (FOX) { if (tid < 64) *(float*)(base + KBYTES + VBYTES + tid * 4) = br; }
;     };
;     const int jlast = nkt - 1;
;     gload(jlast); lstore(0);
;     __syncthreads();
;     m = -1e30f;
.Lmp_745:
	s_or_b64 exec, exec, s[10:11]
	s_and_b32 s10, s13, 0x1fc0
	v_add_u32_e32 v1, s12, v151
	v_subrev_u32_e32 v219, s10, v1
	v_add_u32_e32 v1, s10, v184
	s_xor_b64 s[48:49], s[8:9], -1
	v_mad_i64_i32 v[176:177], s[8:9], v1, s70, v[172:173]
	v_add_u32_e32 v1, s10, v189
	v_mov_b32_e32 v14, v0
	v_mov_b32_e32 v15, v0
	v_mad_i64_i32 v[178:179], s[8:9], v1, s70, v[174:175]
	v_mov_b32_e32 v1, v0
	v_mov_b32_e32 v2, v0
	v_mov_b32_e32 v3, v0
	v_mov_b32_e32 v4, v0
	v_mov_b32_e32 v5, v0
	v_mov_b32_e32 v6, v0
	v_mov_b32_e32 v7, v0
	v_mov_b32_e32 v8, v0
	v_mov_b32_e32 v9, v0
	v_mov_b32_e32 v10, v0
	v_mov_b32_e32 v11, v0
	v_mov_b32_e32 v12, v0
	v_mov_b32_e32 v13, v0
	v_mov_b64_e32 v[32:33], v[14:15]
	v_mov_b64_e32 v[30:31], v[12:13]
	v_mov_b64_e32 v[28:29], v[10:11]
	v_mov_b64_e32 v[26:27], v[8:9]
	v_mov_b64_e32 v[24:25], v[6:7]
	v_mov_b64_e32 v[22:23], v[4:5]
	v_mov_b64_e32 v[20:21], v[2:3]
	v_mov_b64_e32 v[18:19], v[0:1]
	v_mov_b64_e32 v[16:17], v[14:15]
	s_lshr_b32 s2, s13, 6
	v_add_u32_e32 v218, 31, v159
	v_readfirstlane_b32 s73, v159
	s_nop 1
	s_add_i32 s72, s73, 31
	s_sub_i32 s42, s10, 64
	s_mov_b32 s60, 0
	v_mov_b32_e32 v220, 0
	v_mov_b32_e32 v248, 0
	v_mov_b32_e32 v249, 0
	v_mov_b32_e32 v250, 0
	v_mov_b32_e32 v251, 0
	v_mov_b32_e32 v252, 0
	v_mov_b32_e32 v253, 0
	v_mov_b32_e32 v254, 0
	v_mov_b32_e32 v255, 0
	v_mov_b32_e32 v221, 0xf149f2ca
	v_mov_b32_e32 v230, 0
	v_mov_b32_e32 v231, 0
	v_mov_b32_e32 v232, 0
	v_mov_b32_e32 v233, 0
	v_mov_b32_e32 v234, 0
	v_mov_b32_e32 v235, 0
	v_mov_b32_e32 v236, 0
	v_mov_b32_e32 v237, 0
	v_mov_b32_e32 v238, 0
	v_mov_b32_e32 v239, 0
	v_mov_b32_e32 v240, 0
	v_mov_b32_e32 v241, 0
	v_mov_b32_e32 v242, 0
	v_mov_b32_e32 v243, 0
	v_mov_b32_e32 v244, 0
	v_mov_b32_e32 v245, 0
	v_mov_b32_e32 v246, 0
	v_mov_b64_e32 v[14:15], v[12:13]
	v_mov_b64_e32 v[12:13], v[10:11]
	v_mov_b64_e32 v[10:11], v[8:9]
	v_mov_b64_e32 v[8:9], v[6:7]
	v_mov_b64_e32 v[6:7], v[4:5]
	v_mov_b64_e32 v[4:5], v[2:3]
	v_mov_b64_e32 v[2:3], v[0:1]
	s_waitcnt vmcnt(4)
	ds_write2_b64 v213, v[98:99], v[100:101] offset1:1
	s_waitcnt lgkmcnt(0)
	s_barrier
	s_branch .LBB0_748

;     ...
;         if (!wdone && 64 * j <= qw0 + 31) {
;             const unsigned char* kb = lds + st * STG;
;             const unsigned char* vb = kb + KBYTES;
;             f32x16 s[2];
;             if (FOX) {
;                 const float* bl = (const float*)(vb + VBYTES);
; #pragma unroll
;                 for (int t2 = 0; t2 < 2; ++t2)
; #pragma unroll
;                     for (int g = 0; g < 4; ++g) {
;                         const f32x4 b4 = *(const f32x4*)(bl + t2 * 32 + 8 * g + 4 * h);
;                         s[t2][4 * g] = b4[0]; s[t2][4 * g + 1] = b4[1]; s[t2][4 * g + 2] = b4[2]; s[t2][4 * g + 3] = b4[3];
;                     }
;             } else {
; #pragma unroll
;                 for (int t2 = 0; t2 < 2; ++t2)
; #pragma unroll
;                     for (int r = 0; r < 16; ++r) s[t2][r] = 0.f;
;             }
;             bf16x8 kf[KS][2];
; #pragma unroll
;             for (int ks = 0; ks < KS; ++ks)
; #pragma unroll
;                 for (int t2 = 0; t2 < 2; ++t2) kf[ks][t2] = *(const bf16x8*)(kb + (t2 * 32 + ln) * KROW + ks * 32 + h * 16);
;             __builtin_amdgcn_sched_barrier(0);
; #pragma unroll
;             for (int ks = 0; ks < KS; ++ks)
; #pragma unroll
;                 for (int t2 = 0; t2 < 2; ++t2) s[t2] = __builtin_amdgcn_mfma_f32_32x32x16_bf16(kf[ks][t2], qf[ks], s[t2], 0, 0, 0);
;             __builtin_amdgcn_sched_barrier(0);
;             u32x2 vf[4][2][2];
; #pragma unroll
;             for (int kk = 0; kk < 4; ++kk)
; #pragma unroll
;                 for (int d = 0; d < 2; ++d) {
;                     const unsigned char* va = vb + (d * 32 + ln) * VROW + (16 * kk + 4 * h) * 2;
;                     vf[kk][d][0] = *(const u32x2*)va; vf[kk][d][1] = *(const u32x2*)(va + 16);
;                 }
;             __builtin_amdgcn_sched_barrier(0);
;             if (64 * j + 63 > qw0) {
;                 const int thr = myq - 64 * j - 4 * h;
; #pragma unroll
;                 for (int t2 = 0; t2 < 2; ++t2)
; #pragma unroll
;                     for (int r = 0; r < 16; ++r) { if (((r & 3) + 8 * (r >> 2) + 32 * t2) > thr) s[t2][r] = -INFINITY; }
;             }
.LBB0_754:
	s_add_i32 s8, s42, 64
	s_and_b32 s61, s60, 1
	s_mov_b64 s[66:67], exec
	s_cmp_le_i32 s8, s72
	s_cbranch_scc0 .LBB0_760
	s_mul_i32 s8, s61, 0x5700
	s_add_i32 s8, s8, 0
	v_add3_u32 v1, s8, v150, v200
	ds_read_b128 v[34:37], v1 offset:2048
	ds_read_b128 v[102:105], v1 offset:2080
	ds_read_b128 v[38:41], v1 offset:8704
	ds_read_b128 v[106:109], v1 offset:8736
	ds_read_b128 v[110:113], v1 offset:2112
	ds_read_b128 v[114:117], v1 offset:2144
	ds_read_b128 v[118:121], v1 offset:8768
	ds_read_b128 v[122:125], v1 offset:8800
	ds_read_b128 v[126:129], v1 offset:2176
	ds_read_b128 v[130:133], v1 offset:2208
	ds_read_b128 v[222:225], v1 offset:8832
	ds_read_b128 v[226:229], v1 offset:8864
	s_waitcnt lgkmcnt(11)
	v_mfma_f32_32x32x16_bf16 v[50:65], v[34:37], v[66:69], v[230:245]
	s_waitcnt lgkmcnt(9)
	v_mfma_f32_32x32x16_bf16 v[34:49], v[38:41], v[66:69], v[230:245]
	v_mfma_f32_32x32x16_bf16 v[50:65], v[102:105], v[70:73], v[50:65]
	s_waitcnt lgkmcnt(8)
	v_mfma_f32_32x32x16_bf16 v[34:49], v[106:109], v[70:73], v[34:49]
	s_waitcnt lgkmcnt(7)
	v_mfma_f32_32x32x16_bf16 v[50:65], v[110:113], v[74:77], v[50:65]
	s_waitcnt lgkmcnt(5)
	v_mfma_f32_32x32x16_bf16 v[34:49], v[118:121], v[74:77], v[34:49]
	v_mfma_f32_32x32x16_bf16 v[50:65], v[114:117], v[78:81], v[50:65]
	s_waitcnt lgkmcnt(4)
	v_mfma_f32_32x32x16_bf16 v[34:49], v[122:125], v[78:81], v[34:49]
	s_waitcnt lgkmcnt(3)
	v_mfma_f32_32x32x16_bf16 v[50:65], v[126:129], v[82:85], v[50:65]
	s_waitcnt lgkmcnt(1)
	v_mfma_f32_32x32x16_bf16 v[34:49], v[222:225], v[82:85], v[34:49]
	v_mfma_f32_32x32x16_bf16 v[50:65], v[130:133], v[86:89], v[50:65]
	s_waitcnt lgkmcnt(0)
	v_mfma_f32_32x32x16_bf16 v[34:49], v[226:229], v[86:89], v[34:49]
	v_add3_u32 v1, s8, v152, v181
	v_add_u32_e32 v102, 0x3800, v1
	v_add_u32_e32 v1, 0x4800, v1
	ds_read2_b64 v[130:133], v102 offset0:128 offset1:130
	ds_read2_b64 v[122:125], v102 offset0:132 offset1:134
	ds_read2_b64 v[126:129], v1 offset0:160 offset1:162
	ds_read2_b64 v[118:121], v1 offset0:164 offset1:166
	ds_read2_b64 v[114:117], v102 offset0:136 offset1:138
	ds_read2_b64 v[110:113], v1 offset0:168 offset1:170
	ds_read2_b64 v[106:109], v102 offset0:140 offset1:142
	ds_read2_b64 v[102:105], v1 offset0:172 offset1:174
	s_add_i32 s8, s42, 0x7f
	s_mov_b64 s[68:69], exec
	s_cmp_gt_i32 s8, s73
	s_cbranch_scc0 .LBB0_757
	v_cmp_gt_i32_e32 vcc, 0, v219
	v_cmp_gt_i32_e64 s[8:9], 1, v219
	s_and_b64 vcc, s[8:9], vcc
	v_cndmask_b32_e32 v50, v50, v217, vcc
	v_cmp_lt_i32_e32 vcc, 1, v219
	v_cmp_gt_i32_e64 s[38:39], 58, v219
	v_cmp_gt_i32_e64 s[40:41], 59, v219
	v_cndmask_b32_e32 v52, v217, v52, vcc
	v_cmp_lt_i32_e32 vcc, 2, v219
	v_cmp_gt_i32_e64 s[36:37], 57, v219
	s_and_b64 s[38:39], s[40:41], s[38:39]
	v_cndmask_b32_e32 v53, v217, v53, vcc
	v_cmp_lt_i32_e32 vcc, 7, v219
	v_cmp_gt_i32_e64 s[34:35], 56, v219
	s_and_b64 s[36:37], s[38:39], s[36:37]
	v_cndmask_b32_e32 v54, v217, v54, vcc
	v_cmp_lt_i32_e32 vcc, 8, v219
	v_cmp_gt_i32_e64 s[30:31], 51, v219
	s_and_b64 s[34:35], s[36:37], s[34:35]
	v_cndmask_b32_e32 v55, v217, v55, vcc
	v_cmp_lt_i32_e32 vcc, 9, v219
	v_cmp_gt_i32_e64 s[28:29], 50, v219
	s_and_b64 s[30:31], s[34:35], s[30:31]
	v_cndmask_b32_e32 v56, v217, v56, vcc
	v_cmp_lt_i32_e32 vcc, 10, v219
	v_cmp_gt_i32_e64 s[26:27], 49, v219
	s_and_b64 s[28:29], s[30:31], s[28:29]
	v_cndmask_b32_e32 v57, v217, v57, vcc
	v_cmp_lt_i32_e32 vcc, 15, v219
	v_cmp_gt_i32_e64 s[24:25], 48, v219
	s_and_b64 s[26:27], s[28:29], s[26:27]
	v_cndmask_b32_e32 v58, v217, v58, vcc
	v_cmp_lt_i32_e32 vcc, 16, v219
	v_cmp_gt_i32_e64 s[22:23], 43, v219
	s_and_b64 s[24:25], s[26:27], s[24:25]
	v_cndmask_b32_e32 v59, v217, v59, vcc
	v_cmp_lt_i32_e32 vcc, 17, v219
	v_cmp_gt_i32_e64 s[20:21], 42, v219
	s_and_b64 s[22:23], s[24:25], s[22:23]
	v_cndmask_b32_e32 v60, v217, v60, vcc
	v_cmp_lt_i32_e32 vcc, 18, v219
	v_cmp_gt_i32_e64 s[18:19], 41, v219
	s_and_b64 s[20:21], s[22:23], s[20:21]
	v_cndmask_b32_e32 v61, v217, v61, vcc
	v_cmp_lt_i32_e32 vcc, 23, v219
	v_cmp_gt_i32_e64 s[14:15], 40, v219
	s_and_b64 s[18:19], s[20:21], s[18:19]
	v_cndmask_b32_e32 v62, v217, v62, vcc
	v_cmp_lt_i32_e32 vcc, 24, v219
	v_cmp_gt_i32_e64 s[12:13], 35, v219
	s_and_b64 s[14:15], s[18:19], s[14:15]
	v_cndmask_b32_e32 v63, v217, v63, vcc
	v_cmp_lt_i32_e32 vcc, 25, v219
	v_cmp_gt_i32_e64 s[10:11], 34, v219
	s_and_b64 s[12:13], s[14:15], s[12:13]
	v_cndmask_b32_e64 v51, v51, v217, s[8:9]
	v_cndmask_b32_e32 v64, v217, v64, vcc
	v_cmp_lt_i32_e32 vcc, 26, v219
	v_cmp_gt_i32_e64 s[8:9], 33, v219
	s_and_b64 s[10:11], s[12:13], s[10:11]
	v_cndmask_b32_e32 v1, v217, v65, vcc
	v_cmp_gt_i32_e32 vcc, 32, v219
	s_and_b64 s[8:9], s[10:11], s[8:9]
	s_and_b64 vcc, s[8:9], vcc
	v_cndmask_b32_e64 v49, v49, v217, s[40:41]
	v_cndmask_b32_e64 v48, v48, v217, s[38:39]
	v_cndmask_b32_e64 v47, v47, v217, s[36:37]
	v_cndmask_b32_e64 v46, v46, v217, s[34:35]
	v_cndmask_b32_e64 v45, v45, v217, s[30:31]
	v_cndmask_b32_e64 v44, v44, v217, s[28:29]
	v_cndmask_b32_e64 v43, v43, v217, s[26:27]
	v_cndmask_b32_e64 v42, v42, v217, s[24:25]
	v_cndmask_b32_e64 v41, v41, v217, s[22:23]
	v_cndmask_b32_e64 v40, v40, v217, s[20:21]
	v_cndmask_b32_e64 v39, v39, v217, s[18:19]
	v_cndmask_b32_e64 v38, v38, v217, s[14:15]
	v_cndmask_b32_e64 v37, v37, v217, s[12:13]
	v_cndmask_b32_e64 v36, v36, v217, s[10:11]
	v_cndmask_b32_e64 v35, v35, v217, s[8:9]
	v_cndmask_b32_e32 v65, v65, v1, vcc
	v_cndmask_b32_e32 v34, v34, v217, vcc
